# nt cache hint on once-streamed f32 traffic (out-proj residual loads / out stores, final norm, prologue x loads)
# speedup vs baseline: 1.0390x; 1.0075x over previous
; __global__ void __launch_bounds__(512, 2) hybrid_fwd(Params p) {
;     ...
;             if (row < T) {
; #pragma unroll
;                 for (int j = 0; j < 4; ++j) va[j] = ((const f32x4*)(p.x + (size_t)row * DM) + lane)[64 * j];
;             }
;             while (row < T) {
;                 const int rn_ = row + NGW; const bool hn = rn_ < T;
;                 if (hn) {
; #pragma unroll
;                     for (int j = 0; j < 4; ++j) vb[j] = ((const f32x4*)(p.x + (size_t)rn_ * DM) + lane)[64 * j];
.LBB0_113:
	s_load_dwordx2 s[8:9], s[92:93], 0x0
	s_andn2_b64 vcc, exec, s[12:13]
	s_cbranch_vccnz .LBB0_115
	s_ashr_i32 s17, s16, 31
	s_lshl_b64 s[12:13], s[16:17], 12
	s_waitcnt lgkmcnt(0)
	s_add_u32 s12, s8, s12
	s_addc_u32 s13, s9, s13
	s_waitcnt vmcnt(3)
	v_lshlrev_b32_e32 v16, 4, v72
	global_load_dwordx4 v[0:3], v16, s[12:13] nt
	global_load_dwordx4 v[4:7], v16, s[12:13] offset:1024 nt
	global_load_dwordx4 v[8:11], v16, s[12:13] offset:2048 nt
	global_load_dwordx4 v[12:15], v16, s[12:13] offset:3072 nt

; __global__ void __launch_bounds__(512, 2) hybrid_fwd(Params p) {
;     ...
;             while (row < T) {
;                 const int rn_ = row + NGW; const bool hn = rn_ < T;
;                 if (hn) {
; #pragma unroll
;                     for (int j = 0; j < 4; ++j) vb[j] = ((const f32x4*)(p.x + (size_t)rn_ * DM) + lane)[64 * j];
;                 }
.LBB0_119:
	s_cmpk_gt_i32 s16, 0x7fff
	s_mov_b64 s[12:13], -1
	s_cbranch_scc1 .LBB0_118
	s_add_i32 s18, s16, s91
	s_cmp_lt_i32 s18, 0x8000
	s_cselect_b64 s[20:21], -1, 0
	s_cmpk_gt_i32 s18, 0x7fff
	s_cbranch_scc1 .LBB0_122
	s_ashr_i32 s19, s18, 31
	s_lshl_b64 s[12:13], s[18:19], 12
	v_lshl_add_u64 v[40:41], v[34:35], 0, s[12:13]
	global_load_dwordx4 v[16:19], v[40:41], off nt
	global_load_dwordx4 v[20:23], v[40:41], off offset:1024 nt
	global_load_dwordx4 v[24:27], v[40:41], off offset:2048 nt
	global_load_dwordx4 v[28:31], v[40:41], off offset:3072 nt

; __global__ void __launch_bounds__(512, 2) hybrid_fwd(Params p) {
;     ...
;                 const int rn2_ = rn_ + NGW; const bool hn2 = rn2_ < T;
;                 if (hn2) {
; #pragma unroll
;                     for (int j = 0; j < 4; ++j) va[j] = ((const f32x4*)(p.x + (size_t)rn2_ * DM) + lane)[64 * j];
;                 }
.LBB0_124:
	s_or_b64 exec, exec, s[12:13]
	s_andn2_b64 vcc, exec, s[20:21]
	s_mov_b64 s[20:21], 0
	s_cbranch_vccnz .LBB0_117
	s_add_i32 s22, s18, s91
	s_cmp_lt_i32 s22, 0x8000
	s_cselect_b64 s[20:21], -1, 0
	s_cmpk_gt_i32 s22, 0x7fff
	s_cbranch_scc1 .LBB0_127
	s_ashr_i32 s23, s22, 31
	s_lshl_b64 s[12:13], s[22:23], 12
	v_lshl_add_u64 v[46:47], v[34:35], 0, s[12:13]
	global_load_dwordx4 v[0:3], v[46:47], off nt
	global_load_dwordx4 v[4:7], v[46:47], off offset:1024 nt
	global_load_dwordx4 v[8:11], v[46:47], off offset:2048 nt
	global_load_dwordx4 v[12:15], v[46:47], off offset:3072 nt

; DI unsigned cvtpk(float lo, float hi) { typedef float f2 __attribute__((ext_vector_type(2))); typedef __bf16 b2 __attribute__((ext_vector_type(2))); f2 v = {lo, hi}; b2 b = __builtin_convertvector(v, b2); return __builtin_bit_cast(unsigned, b); }
;     DI void operator()(f32x4 (&acc)[2][2][4][2], const pg8::GUnit& u, int wr, int wc, int fr, int fq) const {
;     ...
; #pragma unroll
;         for (int ai = 0; ai < 2; ++ai)
; #pragma unroll
;             for (int m = 0; m < 4; ++m) {
;                 const int row = row0 + ai * 128 + m * 16;
;                 const size_t off = (size_t)row * DM + col0;
;                 float q = 0.f;
; #pragma unroll
;                 for (int bj = 0; bj < 2; ++bj) {
;                     const f32x4 b0 = *(const f32x4*)(resid + off + bj * 128), b1 = *(const f32x4*)(resid + off + bj * 128 + 4);
;                     const f32x4 v0 = b0 + acc[ai][bj][m][0], v1 = b1 + acc[ai][bj][m][1];
;                     *(f32x4*)(out + off + bj * 128) = v0; *(f32x4*)(out + off + bj * 128 + 4) = v1;
;                     q += (v0[0] * v0[0] + v0[1] * v0[1]) + (v0[2] * v0[2] + v0[3] * v0[3]) + (v1[0] * v1[0] + v1[1] * v1[1]) + (v1[2] * v1[2] + v1[3] * v1[3]);
;                     if (!last) { u32x4 w; w.x = cvtpk(v0[0], v0[1]); w.y = cvtpk(v0[2], v0[3]); w.z = cvtpk(v1[0], v1[1]); w.w = cvtpk(v1[2], v1[3]);
;                         *(u32x4*)(act + (size_t)row * PITCH + XB_COL + col0 + bj * 128) = w; }
;                 }
.LBB0_805:
	v_lshl_add_u32 v142, s55, 8, v150
	v_lshl_or_b32 v140, s38, 8, v152
	v_ashrrev_i32_e32 v143, 31, v142
	v_ashrrev_i32_e32 v141, 31, v140
	v_lshlrev_b64 v[144:145], 10, v[142:143]
	v_lshl_add_u64 v[144:145], v[144:145], 0, v[140:141]
	v_lshlrev_b64 v[148:149], 2, v[144:145]
	v_lshl_add_u64 v[146:147], s[12:13], 0, v[148:149]
	global_load_dwordx4 v[154:157], v[146:147], off nt
	global_load_dwordx4 v[158:161], v[146:147], off offset:16 nt
	v_readlane_b32 s24, v249, 4
	v_readlane_b32 s25, v249, 5
	v_mad_i64_i32 v[144:145], s[22:23], v142, s31, 0
	s_nop 0
	v_cndmask_b32_e64 v162, 0, 1, s[24:25]
	v_cmp_ne_u32_e64 s[44:45], 1, v162
	s_andn2_b64 vcc, exec, s[24:25]
	v_lshl_add_u64 v[148:149], s[84:85], 0, v[148:149]
	s_waitcnt vmcnt(0)
	v_pk_add_f32 v[128:129], v[128:129], v[156:157]
	v_pk_add_f32 v[126:127], v[126:127], v[154:155]
	v_pk_add_f32 v[124:125], v[124:125], v[160:161]
	v_pk_add_f32 v[122:123], v[122:123], v[158:159]
	global_store_dwordx4 v[148:149], v[126:129], off nt
	global_store_dwordx4 v[148:149], v[122:125], off offset:16 nt
	s_cbranch_vccnz .LBB0_807
	v_lshl_add_u64 v[158:159], s[6:7], 0, v[144:145]
	v_lshl_add_u64 v[158:159], v[140:141], 1, v[158:159]
	v_add_co_u32_e32 v158, vcc, 0x2000, v158
	v_cvt_pk_bf16_f32 v154, v126, v127
	v_cvt_pk_bf16_f32 v155, v128, v129
	v_cvt_pk_bf16_f32 v156, v122, v123
	v_cvt_pk_bf16_f32 v157, v124, v125
	v_addc_co_u32_e32 v159, vcc, 0, v159, vcc
	global_store_dwordx4 v[158:159], v[154:157], off offset:2560
.LBB0_807:
	global_load_dwordx4 v[154:157], v[146:147], off offset:512 nt
	s_nop 0
	global_load_dwordx4 v[158:161], v[146:147], off offset:528 nt
	s_and_b64 vcc, exec, s[44:45]
	s_waitcnt vmcnt(1)
	v_pk_add_f32 v[120:121], v[120:121], v[156:157]
	v_pk_add_f32 v[118:119], v[118:119], v[154:155]
	s_waitcnt vmcnt(0)
	v_pk_add_f32 v[116:117], v[116:117], v[160:161]
	v_pk_add_f32 v[114:115], v[114:115], v[158:159]
	global_store_dwordx4 v[148:149], v[118:121], off offset:512 nt
	global_store_dwordx4 v[148:149], v[114:117], off offset:528 nt
	s_cbranch_vccnz .LBB0_809
	v_lshl_add_u64 v[144:145], s[6:7], 0, v[144:145]
	v_lshl_add_u64 v[144:145], v[140:141], 1, v[144:145]
	v_add_co_u32_e32 v144, vcc, 0x2000, v144
	v_cvt_pk_bf16_f32 v146, v118, v119
	v_cvt_pk_bf16_f32 v147, v120, v121
	v_cvt_pk_bf16_f32 v148, v114, v115
	v_cvt_pk_bf16_f32 v149, v116, v117
	v_addc_co_u32_e32 v145, vcc, 0, v145, vcc
	global_store_dwordx4 v[144:145], v[146:149], off offset:2816

; DI unsigned cvtpk(float lo, float hi) { typedef float f2 __attribute__((ext_vector_type(2))); typedef __bf16 b2 __attribute__((ext_vector_type(2))); f2 v = {lo, hi}; b2 b = __builtin_convertvector(v, b2); return __builtin_bit_cast(unsigned, b); }
;     DI void operator()(f32x4 (&acc)[2][2][4][2], const pg8::GUnit& u, int wr, int wc, int fr, int fq) const {
;     ...
; #pragma unroll
;         for (int ai = 0; ai < 2; ++ai)
; #pragma unroll
;             for (int m = 0; m < 4; ++m) {
;                 const int row = row0 + ai * 128 + m * 16;
;                 const size_t off = (size_t)row * DM + col0;
;                 float q = 0.f;
; #pragma unroll
;                 for (int bj = 0; bj < 2; ++bj) {
;                     const f32x4 b0 = *(const f32x4*)(resid + off + bj * 128), b1 = *(const f32x4*)(resid + off + bj * 128 + 4);
;                     const f32x4 v0 = b0 + acc[ai][bj][m][0], v1 = b1 + acc[ai][bj][m][1];
;                     *(f32x4*)(out + off + bj * 128) = v0; *(f32x4*)(out + off + bj * 128 + 4) = v1;
;                     q += (v0[0] * v0[0] + v0[1] * v0[1]) + (v0[2] * v0[2] + v0[3] * v0[3]) + (v1[0] * v1[0] + v1[1] * v1[1]) + (v1[2] * v1[2] + v1[3] * v1[3]);
;                     if (!last) { u32x4 w; w.x = cvtpk(v0[0], v0[1]); w.y = cvtpk(v0[2], v0[3]); w.z = cvtpk(v1[0], v1[1]); w.w = cvtpk(v1[2], v1[3]);
;                         *(u32x4*)(act + (size_t)row * PITCH + XB_COL + col0 + bj * 128) = w; }
;                 }
.LBB0_811:
	s_or_b64 exec, exec, s[24:25]
	v_or_b32_e32 v114, 16, v142
	s_waitcnt lgkmcnt(0)
	v_ashrrev_i32_e32 v115, 31, v114
	v_lshlrev_b64 v[116:117], 10, v[114:115]
	v_lshl_add_u64 v[116:117], v[116:117], 0, v[140:141]
	v_lshlrev_b64 v[120:121], 2, v[116:117]
	v_lshl_add_u64 v[118:119], s[12:13], 0, v[120:121]
	global_load_dwordx4 v[124:127], v[118:119], off nt
	global_load_dwordx4 v[144:147], v[118:119], off offset:16 nt
	s_and_b64 vcc, exec, s[44:45]
	v_mad_i64_i32 v[116:117], s[24:25], v114, s31, 0
	v_lshl_add_u64 v[120:121], s[84:85], 0, v[120:121]
	s_waitcnt vmcnt(1)
	v_pk_add_f32 v[112:113], v[112:113], v[126:127]
	v_pk_add_f32 v[110:111], v[110:111], v[124:125]
	s_waitcnt vmcnt(0)
	v_pk_add_f32 v[108:109], v[108:109], v[146:147]
	v_pk_add_f32 v[106:107], v[106:107], v[144:145]
	global_store_dwordx4 v[120:121], v[110:113], off nt
	global_store_dwordx4 v[120:121], v[106:109], off offset:16 nt
	s_cbranch_vccnz .LBB0_813
	v_lshl_add_u64 v[128:129], s[6:7], 0, v[116:117]
	v_lshl_add_u64 v[128:129], v[140:141], 1, v[128:129]
	v_add_co_u32_e32 v128, vcc, 0x2000, v128
	v_cvt_pk_bf16_f32 v124, v110, v111
	v_cvt_pk_bf16_f32 v125, v112, v113
	v_cvt_pk_bf16_f32 v126, v106, v107
	v_cvt_pk_bf16_f32 v127, v108, v109
	v_addc_co_u32_e32 v129, vcc, 0, v129, vcc
	global_store_dwordx4 v[128:129], v[124:127], off offset:2560
.LBB0_813:
	global_load_dwordx4 v[124:127], v[118:119], off offset:512 nt
	s_nop 0
	global_load_dwordx4 v[144:147], v[118:119], off offset:528 nt
	s_and_b64 vcc, exec, s[44:45]
	s_waitcnt vmcnt(1)
	v_pk_add_f32 v[104:105], v[104:105], v[126:127]
	v_pk_add_f32 v[102:103], v[102:103], v[124:125]
	s_waitcnt vmcnt(0)
	v_pk_add_f32 v[100:101], v[100:101], v[146:147]
	v_pk_add_f32 v[98:99], v[98:99], v[144:145]
	global_store_dwordx4 v[120:121], v[102:105], off offset:512 nt
	global_store_dwordx4 v[120:121], v[98:101], off offset:528 nt
	s_cbranch_vccnz .LBB0_815
	v_lshl_add_u64 v[116:117], s[6:7], 0, v[116:117]
	v_lshl_add_u64 v[116:117], v[140:141], 1, v[116:117]
	v_add_co_u32_e32 v116, vcc, 0x2000, v116
	v_cvt_pk_bf16_f32 v118, v102, v103
	v_cvt_pk_bf16_f32 v119, v104, v105
	v_cvt_pk_bf16_f32 v120, v98, v99
	v_cvt_pk_bf16_f32 v121, v100, v101
	v_addc_co_u32_e32 v117, vcc, 0, v117, vcc
	global_store_dwordx4 v[116:117], v[118:121], off offset:2816

; DI unsigned cvtpk(float lo, float hi) { typedef float f2 __attribute__((ext_vector_type(2))); typedef __bf16 b2 __attribute__((ext_vector_type(2))); f2 v = {lo, hi}; b2 b = __builtin_convertvector(v, b2); return __builtin_bit_cast(unsigned, b); }
;     DI void operator()(f32x4 (&acc)[2][2][4][2], const pg8::GUnit& u, int wr, int wc, int fr, int fq) const {
;     ...
; #pragma unroll
;         for (int ai = 0; ai < 2; ++ai)
; #pragma unroll
;             for (int m = 0; m < 4; ++m) {
;                 const int row = row0 + ai * 128 + m * 16;
;                 const size_t off = (size_t)row * DM + col0;
;                 float q = 0.f;
; #pragma unroll
;                 for (int bj = 0; bj < 2; ++bj) {
;                     const f32x4 b0 = *(const f32x4*)(resid + off + bj * 128), b1 = *(const f32x4*)(resid + off + bj * 128 + 4);
;                     const f32x4 v0 = b0 + acc[ai][bj][m][0], v1 = b1 + acc[ai][bj][m][1];
;                     *(f32x4*)(out + off + bj * 128) = v0; *(f32x4*)(out + off + bj * 128 + 4) = v1;
;                     q += (v0[0] * v0[0] + v0[1] * v0[1]) + (v0[2] * v0[2] + v0[3] * v0[3]) + (v1[0] * v1[0] + v1[1] * v1[1]) + (v1[2] * v1[2] + v1[3] * v1[3]);
;                     if (!last) { u32x4 w; w.x = cvtpk(v0[0], v0[1]); w.y = cvtpk(v0[2], v0[3]); w.z = cvtpk(v1[0], v1[1]); w.w = cvtpk(v1[2], v1[3]);
;                         *(u32x4*)(act + (size_t)row * PITCH + XB_COL + col0 + bj * 128) = w; }
;                 }
.LBB0_817:
	s_or_b64 exec, exec, s[24:25]
	v_or_b32_e32 v98, 32, v142
	s_waitcnt lgkmcnt(0)
	v_ashrrev_i32_e32 v99, 31, v98
	v_lshlrev_b64 v[100:101], 10, v[98:99]
	v_lshl_add_u64 v[100:101], v[100:101], 0, v[140:141]
	v_lshlrev_b64 v[104:105], 2, v[100:101]
	v_lshl_add_u64 v[102:103], s[12:13], 0, v[104:105]
	global_load_dwordx4 v[106:109], v[102:103], off nt
	global_load_dwordx4 v[110:113], v[102:103], off offset:16 nt
	s_and_b64 vcc, exec, s[44:45]
	v_mad_i64_i32 v[100:101], s[24:25], v98, s31, 0
	v_lshl_add_u64 v[104:105], s[84:85], 0, v[104:105]
	s_waitcnt vmcnt(1)
	v_pk_add_f32 v[96:97], v[96:97], v[108:109]
	v_pk_add_f32 v[94:95], v[94:95], v[106:107]
	s_waitcnt vmcnt(0)
	v_pk_add_f32 v[92:93], v[92:93], v[112:113]
	v_pk_add_f32 v[90:91], v[90:91], v[110:111]
	global_store_dwordx4 v[104:105], v[94:97], off nt
	global_store_dwordx4 v[104:105], v[90:93], off offset:16 nt
	s_cbranch_vccnz .LBB0_819
	v_lshl_add_u64 v[110:111], s[6:7], 0, v[100:101]
	v_lshl_add_u64 v[110:111], v[140:141], 1, v[110:111]
	v_add_co_u32_e32 v110, vcc, 0x2000, v110
	v_cvt_pk_bf16_f32 v106, v94, v95
	v_cvt_pk_bf16_f32 v107, v96, v97
	v_cvt_pk_bf16_f32 v108, v90, v91
	v_cvt_pk_bf16_f32 v109, v92, v93
	v_addc_co_u32_e32 v111, vcc, 0, v111, vcc
	global_store_dwordx4 v[110:111], v[106:109], off offset:2560
.LBB0_819:
	global_load_dwordx4 v[106:109], v[102:103], off offset:512 nt
	s_nop 0
	global_load_dwordx4 v[110:113], v[102:103], off offset:528 nt
	s_and_b64 vcc, exec, s[44:45]
	s_waitcnt vmcnt(1)
	v_pk_add_f32 v[88:89], v[88:89], v[108:109]
	v_pk_add_f32 v[86:87], v[86:87], v[106:107]
	s_waitcnt vmcnt(0)
	v_pk_add_f32 v[84:85], v[84:85], v[112:113]
	v_pk_add_f32 v[82:83], v[82:83], v[110:111]
	global_store_dwordx4 v[104:105], v[86:89], off offset:512 nt
	global_store_dwordx4 v[104:105], v[82:85], off offset:528 nt
	s_cbranch_vccnz .LBB0_821
	v_lshl_add_u64 v[100:101], s[6:7], 0, v[100:101]
	v_lshl_add_u64 v[100:101], v[140:141], 1, v[100:101]
	v_add_co_u32_e32 v100, vcc, 0x2000, v100
	v_cvt_pk_bf16_f32 v102, v86, v87
	v_cvt_pk_bf16_f32 v103, v88, v89
	v_cvt_pk_bf16_f32 v104, v82, v83
	v_cvt_pk_bf16_f32 v105, v84, v85
	v_addc_co_u32_e32 v101, vcc, 0, v101, vcc
	global_store_dwordx4 v[100:101], v[102:105], off offset:2816

; DI unsigned cvtpk(float lo, float hi) { typedef float f2 __attribute__((ext_vector_type(2))); typedef __bf16 b2 __attribute__((ext_vector_type(2))); f2 v = {lo, hi}; b2 b = __builtin_convertvector(v, b2); return __builtin_bit_cast(unsigned, b); }
;     DI void operator()(f32x4 (&acc)[2][2][4][2], const pg8::GUnit& u, int wr, int wc, int fr, int fq) const {
;     ...
; #pragma unroll
;         for (int ai = 0; ai < 2; ++ai)
; #pragma unroll
;             for (int m = 0; m < 4; ++m) {
;                 const int row = row0 + ai * 128 + m * 16;
;                 const size_t off = (size_t)row * DM + col0;
;                 float q = 0.f;
; #pragma unroll
;                 for (int bj = 0; bj < 2; ++bj) {
;                     const f32x4 b0 = *(const f32x4*)(resid + off + bj * 128), b1 = *(const f32x4*)(resid + off + bj * 128 + 4);
;                     const f32x4 v0 = b0 + acc[ai][bj][m][0], v1 = b1 + acc[ai][bj][m][1];
;                     *(f32x4*)(out + off + bj * 128) = v0; *(f32x4*)(out + off + bj * 128 + 4) = v1;
;                     q += (v0[0] * v0[0] + v0[1] * v0[1]) + (v0[2] * v0[2] + v0[3] * v0[3]) + (v1[0] * v1[0] + v1[1] * v1[1]) + (v1[2] * v1[2] + v1[3] * v1[3]);
;                     if (!last) { u32x4 w; w.x = cvtpk(v0[0], v0[1]); w.y = cvtpk(v0[2], v0[3]); w.z = cvtpk(v1[0], v1[1]); w.w = cvtpk(v1[2], v1[3]);
;                         *(u32x4*)(act + (size_t)row * PITCH + XB_COL + col0 + bj * 128) = w; }
;                 }
.LBB0_823:
	s_or_b64 exec, exec, s[24:25]
	v_or_b32_e32 v82, 48, v142
	s_waitcnt lgkmcnt(0)
	v_ashrrev_i32_e32 v83, 31, v82
	v_lshlrev_b64 v[84:85], 10, v[82:83]
	v_lshl_add_u64 v[84:85], v[84:85], 0, v[140:141]
	v_lshlrev_b64 v[88:89], 2, v[84:85]
	v_lshl_add_u64 v[86:87], s[12:13], 0, v[88:89]
	global_load_dwordx4 v[90:93], v[86:87], off nt
	global_load_dwordx4 v[94:97], v[86:87], off offset:16 nt
	s_and_b64 vcc, exec, s[44:45]
	v_mad_i64_i32 v[84:85], s[24:25], v82, s31, 0
	v_lshl_add_u64 v[88:89], s[84:85], 0, v[88:89]
	s_waitcnt vmcnt(1)
	v_pk_add_f32 v[80:81], v[80:81], v[92:93]
	v_pk_add_f32 v[78:79], v[78:79], v[90:91]
	s_waitcnt vmcnt(0)
	v_pk_add_f32 v[76:77], v[76:77], v[96:97]
	v_pk_add_f32 v[74:75], v[74:75], v[94:95]
	global_store_dwordx4 v[88:89], v[78:81], off nt
	global_store_dwordx4 v[88:89], v[74:77], off offset:16 nt
	s_cbranch_vccnz .LBB0_825
	v_lshl_add_u64 v[94:95], s[6:7], 0, v[84:85]
	v_lshl_add_u64 v[94:95], v[140:141], 1, v[94:95]
	v_add_co_u32_e32 v94, vcc, 0x2000, v94
	v_cvt_pk_bf16_f32 v90, v78, v79
	v_cvt_pk_bf16_f32 v91, v80, v81
	v_cvt_pk_bf16_f32 v92, v74, v75
	v_cvt_pk_bf16_f32 v93, v76, v77
	v_addc_co_u32_e32 v95, vcc, 0, v95, vcc
	global_store_dwordx4 v[94:95], v[90:93], off offset:2560
.LBB0_825:
	global_load_dwordx4 v[90:93], v[86:87], off offset:512 nt
	s_nop 0
	global_load_dwordx4 v[94:97], v[86:87], off offset:528 nt
	s_and_b64 vcc, exec, s[44:45]
	s_waitcnt vmcnt(1)
	v_pk_add_f32 v[72:73], v[72:73], v[92:93]
	v_pk_add_f32 v[70:71], v[70:71], v[90:91]
	s_waitcnt vmcnt(0)
	v_pk_add_f32 v[68:69], v[68:69], v[96:97]
	v_pk_add_f32 v[66:67], v[66:67], v[94:95]
	global_store_dwordx4 v[88:89], v[70:73], off offset:512 nt
	global_store_dwordx4 v[88:89], v[66:69], off offset:528 nt
	s_cbranch_vccnz .LBB0_827
	v_lshl_add_u64 v[84:85], s[6:7], 0, v[84:85]
	v_lshl_add_u64 v[84:85], v[140:141], 1, v[84:85]
	v_add_co_u32_e32 v84, vcc, 0x2000, v84
	v_cvt_pk_bf16_f32 v86, v70, v71
	v_cvt_pk_bf16_f32 v87, v72, v73
	v_cvt_pk_bf16_f32 v88, v66, v67
	v_cvt_pk_bf16_f32 v89, v68, v69
	v_addc_co_u32_e32 v85, vcc, 0, v85, vcc
	global_store_dwordx4 v[84:85], v[86:89], off offset:2816

; DI unsigned cvtpk(float lo, float hi) { typedef float f2 __attribute__((ext_vector_type(2))); typedef __bf16 b2 __attribute__((ext_vector_type(2))); f2 v = {lo, hi}; b2 b = __builtin_convertvector(v, b2); return __builtin_bit_cast(unsigned, b); }
;     DI void operator()(f32x4 (&acc)[2][2][4][2], const pg8::GUnit& u, int wr, int wc, int fr, int fq) const {
;     ...
; #pragma unroll
;         for (int ai = 0; ai < 2; ++ai)
; #pragma unroll
;             for (int m = 0; m < 4; ++m) {
;                 const int row = row0 + ai * 128 + m * 16;
;                 const size_t off = (size_t)row * DM + col0;
;                 float q = 0.f;
; #pragma unroll
;                 for (int bj = 0; bj < 2; ++bj) {
;                     const f32x4 b0 = *(const f32x4*)(resid + off + bj * 128), b1 = *(const f32x4*)(resid + off + bj * 128 + 4);
;                     const f32x4 v0 = b0 + acc[ai][bj][m][0], v1 = b1 + acc[ai][bj][m][1];
;                     *(f32x4*)(out + off + bj * 128) = v0; *(f32x4*)(out + off + bj * 128 + 4) = v1;
;                     q += (v0[0] * v0[0] + v0[1] * v0[1]) + (v0[2] * v0[2] + v0[3] * v0[3]) + (v1[0] * v1[0] + v1[1] * v1[1]) + (v1[2] * v1[2] + v1[3] * v1[3]);
;                     if (!last) { u32x4 w; w.x = cvtpk(v0[0], v0[1]); w.y = cvtpk(v0[2], v0[3]); w.z = cvtpk(v1[0], v1[1]); w.w = cvtpk(v1[2], v1[3]);
;                         *(u32x4*)(act + (size_t)row * PITCH + XB_COL + col0 + bj * 128) = w; }
;                 }
.LBB0_829:
	s_or_b64 exec, exec, s[24:25]
	v_add_u32_e32 v66, 0x80, v142
	s_waitcnt lgkmcnt(0)
	v_ashrrev_i32_e32 v67, 31, v66
	v_lshlrev_b64 v[68:69], 10, v[66:67]
	v_lshl_add_u64 v[68:69], v[68:69], 0, v[140:141]
	v_lshlrev_b64 v[72:73], 2, v[68:69]
	v_lshl_add_u64 v[70:71], s[12:13], 0, v[72:73]
	global_load_dwordx4 v[74:77], v[70:71], off nt
	global_load_dwordx4 v[78:81], v[70:71], off offset:16 nt
	s_and_b64 vcc, exec, s[44:45]
	v_mad_i64_i32 v[68:69], s[24:25], v66, s31, 0
	v_lshl_add_u64 v[72:73], s[84:85], 0, v[72:73]
	s_waitcnt vmcnt(1)
	v_pk_add_f32 v[64:65], v[64:65], v[76:77]
	v_pk_add_f32 v[62:63], v[62:63], v[74:75]
	s_waitcnt vmcnt(0)
	v_pk_add_f32 v[60:61], v[60:61], v[80:81]
	v_pk_add_f32 v[58:59], v[58:59], v[78:79]
	global_store_dwordx4 v[72:73], v[62:65], off nt
	global_store_dwordx4 v[72:73], v[58:61], off offset:16 nt
	s_cbranch_vccnz .LBB0_831
	v_lshl_add_u64 v[78:79], s[6:7], 0, v[68:69]
	v_lshl_add_u64 v[78:79], v[140:141], 1, v[78:79]
	v_add_co_u32_e32 v78, vcc, 0x2000, v78
	v_cvt_pk_bf16_f32 v74, v62, v63
	v_cvt_pk_bf16_f32 v75, v64, v65
	v_cvt_pk_bf16_f32 v76, v58, v59
	v_cvt_pk_bf16_f32 v77, v60, v61
	v_addc_co_u32_e32 v79, vcc, 0, v79, vcc
	global_store_dwordx4 v[78:79], v[74:77], off offset:2560
.LBB0_831:
	global_load_dwordx4 v[74:77], v[70:71], off offset:512 nt
	s_nop 0
	global_load_dwordx4 v[78:81], v[70:71], off offset:528 nt
	s_and_b64 vcc, exec, s[44:45]
	s_waitcnt vmcnt(1)
	v_pk_add_f32 v[56:57], v[56:57], v[76:77]
	v_pk_add_f32 v[54:55], v[54:55], v[74:75]
	s_waitcnt vmcnt(0)
	v_pk_add_f32 v[52:53], v[52:53], v[80:81]
	v_pk_add_f32 v[50:51], v[50:51], v[78:79]
	global_store_dwordx4 v[72:73], v[54:57], off offset:512 nt
	global_store_dwordx4 v[72:73], v[50:53], off offset:528 nt
	s_cbranch_vccnz .LBB0_833
	v_lshl_add_u64 v[68:69], s[6:7], 0, v[68:69]
	v_lshl_add_u64 v[68:69], v[140:141], 1, v[68:69]
	v_add_co_u32_e32 v68, vcc, 0x2000, v68
	v_cvt_pk_bf16_f32 v70, v54, v55
	v_cvt_pk_bf16_f32 v71, v56, v57
	v_cvt_pk_bf16_f32 v72, v50, v51
	v_cvt_pk_bf16_f32 v73, v52, v53
	v_addc_co_u32_e32 v69, vcc, 0, v69, vcc
	global_store_dwordx4 v[68:69], v[70:73], off offset:2816

; DI unsigned cvtpk(float lo, float hi) { typedef float f2 __attribute__((ext_vector_type(2))); typedef __bf16 b2 __attribute__((ext_vector_type(2))); f2 v = {lo, hi}; b2 b = __builtin_convertvector(v, b2); return __builtin_bit_cast(unsigned, b); }
;     DI void operator()(f32x4 (&acc)[2][2][4][2], const pg8::GUnit& u, int wr, int wc, int fr, int fq) const {
;     ...
; #pragma unroll
;         for (int ai = 0; ai < 2; ++ai)
; #pragma unroll
;             for (int m = 0; m < 4; ++m) {
;                 const int row = row0 + ai * 128 + m * 16;
;                 const size_t off = (size_t)row * DM + col0;
;                 float q = 0.f;
; #pragma unroll
;                 for (int bj = 0; bj < 2; ++bj) {
;                     const f32x4 b0 = *(const f32x4*)(resid + off + bj * 128), b1 = *(const f32x4*)(resid + off + bj * 128 + 4);
;                     const f32x4 v0 = b0 + acc[ai][bj][m][0], v1 = b1 + acc[ai][bj][m][1];
;                     *(f32x4*)(out + off + bj * 128) = v0; *(f32x4*)(out + off + bj * 128 + 4) = v1;
;                     q += (v0[0] * v0[0] + v0[1] * v0[1]) + (v0[2] * v0[2] + v0[3] * v0[3]) + (v1[0] * v1[0] + v1[1] * v1[1]) + (v1[2] * v1[2] + v1[3] * v1[3]);
;                     if (!last) { u32x4 w; w.x = cvtpk(v0[0], v0[1]); w.y = cvtpk(v0[2], v0[3]); w.z = cvtpk(v1[0], v1[1]); w.w = cvtpk(v1[2], v1[3]);
;                         *(u32x4*)(act + (size_t)row * PITCH + XB_COL + col0 + bj * 128) = w; }
;                 }
.LBB0_835:
	s_or_b64 exec, exec, s[24:25]
	v_add_u32_e32 v50, 0x90, v142
	s_waitcnt lgkmcnt(0)
	v_ashrrev_i32_e32 v51, 31, v50
	v_lshlrev_b64 v[52:53], 10, v[50:51]
	v_lshl_add_u64 v[52:53], v[52:53], 0, v[140:141]
	v_lshlrev_b64 v[56:57], 2, v[52:53]
	v_lshl_add_u64 v[54:55], s[12:13], 0, v[56:57]
	global_load_dwordx4 v[58:61], v[54:55], off nt
	global_load_dwordx4 v[62:65], v[54:55], off offset:16 nt
	s_and_b64 vcc, exec, s[44:45]
	v_mad_i64_i32 v[52:53], s[24:25], v50, s31, 0
	v_lshl_add_u64 v[56:57], s[84:85], 0, v[56:57]
	s_waitcnt vmcnt(1)
	v_pk_add_f32 v[48:49], v[48:49], v[60:61]
	v_pk_add_f32 v[46:47], v[46:47], v[58:59]
	s_waitcnt vmcnt(0)
	v_pk_add_f32 v[44:45], v[44:45], v[64:65]
	v_pk_add_f32 v[42:43], v[42:43], v[62:63]
	global_store_dwordx4 v[56:57], v[46:49], off nt
	global_store_dwordx4 v[56:57], v[42:45], off offset:16 nt
	s_cbranch_vccnz .LBB0_837
	v_lshl_add_u64 v[62:63], s[6:7], 0, v[52:53]
	v_lshl_add_u64 v[62:63], v[140:141], 1, v[62:63]
	v_add_co_u32_e32 v62, vcc, 0x2000, v62
	v_cvt_pk_bf16_f32 v58, v46, v47
	v_cvt_pk_bf16_f32 v59, v48, v49
	v_cvt_pk_bf16_f32 v60, v42, v43
	v_cvt_pk_bf16_f32 v61, v44, v45
	v_addc_co_u32_e32 v63, vcc, 0, v63, vcc
	global_store_dwordx4 v[62:63], v[58:61], off offset:2560
.LBB0_837:
	global_load_dwordx4 v[58:61], v[54:55], off offset:512 nt
	s_nop 0
	global_load_dwordx4 v[62:65], v[54:55], off offset:528 nt
	s_and_b64 vcc, exec, s[44:45]
	s_waitcnt vmcnt(1)
	v_pk_add_f32 v[40:41], v[40:41], v[60:61]
	v_pk_add_f32 v[38:39], v[38:39], v[58:59]
	s_waitcnt vmcnt(0)
	v_pk_add_f32 v[36:37], v[36:37], v[64:65]
	v_pk_add_f32 v[34:35], v[34:35], v[62:63]
	global_store_dwordx4 v[56:57], v[38:41], off offset:512 nt
	global_store_dwordx4 v[56:57], v[34:37], off offset:528 nt
	s_cbranch_vccnz .LBB0_839
	v_lshl_add_u64 v[52:53], s[6:7], 0, v[52:53]
	v_lshl_add_u64 v[52:53], v[140:141], 1, v[52:53]
	v_add_co_u32_e32 v52, vcc, 0x2000, v52
	v_cvt_pk_bf16_f32 v54, v38, v39
	v_cvt_pk_bf16_f32 v55, v40, v41
	v_cvt_pk_bf16_f32 v56, v34, v35
	v_cvt_pk_bf16_f32 v57, v36, v37
	v_addc_co_u32_e32 v53, vcc, 0, v53, vcc
	global_store_dwordx4 v[52:53], v[54:57], off offset:2816

; DI unsigned cvtpk(float lo, float hi) { typedef float f2 __attribute__((ext_vector_type(2))); typedef __bf16 b2 __attribute__((ext_vector_type(2))); f2 v = {lo, hi}; b2 b = __builtin_convertvector(v, b2); return __builtin_bit_cast(unsigned, b); }
;     DI void operator()(f32x4 (&acc)[2][2][4][2], const pg8::GUnit& u, int wr, int wc, int fr, int fq) const {
;     ...
; #pragma unroll
;         for (int ai = 0; ai < 2; ++ai)
; #pragma unroll
;             for (int m = 0; m < 4; ++m) {
;                 const int row = row0 + ai * 128 + m * 16;
;                 const size_t off = (size_t)row * DM + col0;
;                 float q = 0.f;
; #pragma unroll
;                 for (int bj = 0; bj < 2; ++bj) {
;                     const f32x4 b0 = *(const f32x4*)(resid + off + bj * 128), b1 = *(const f32x4*)(resid + off + bj * 128 + 4);
;                     const f32x4 v0 = b0 + acc[ai][bj][m][0], v1 = b1 + acc[ai][bj][m][1];
;                     *(f32x4*)(out + off + bj * 128) = v0; *(f32x4*)(out + off + bj * 128 + 4) = v1;
;                     q += (v0[0] * v0[0] + v0[1] * v0[1]) + (v0[2] * v0[2] + v0[3] * v0[3]) + (v1[0] * v1[0] + v1[1] * v1[1]) + (v1[2] * v1[2] + v1[3] * v1[3]);
;                     if (!last) { u32x4 w; w.x = cvtpk(v0[0], v0[1]); w.y = cvtpk(v0[2], v0[3]); w.z = cvtpk(v1[0], v1[1]); w.w = cvtpk(v1[2], v1[3]);
;                         *(u32x4*)(act + (size_t)row * PITCH + XB_COL + col0 + bj * 128) = w; }
;                 }
.LBB0_841:
	s_or_b64 exec, exec, s[24:25]
	v_add_u32_e32 v34, 0xa0, v142
	s_waitcnt lgkmcnt(0)
	v_ashrrev_i32_e32 v35, 31, v34
	v_lshlrev_b64 v[36:37], 10, v[34:35]
	v_lshl_add_u64 v[36:37], v[36:37], 0, v[140:141]
	v_lshlrev_b64 v[40:41], 2, v[36:37]
	v_lshl_add_u64 v[38:39], s[12:13], 0, v[40:41]
	global_load_dwordx4 v[42:45], v[38:39], off nt
	global_load_dwordx4 v[46:49], v[38:39], off offset:16 nt
	s_and_b64 vcc, exec, s[44:45]
	v_mad_i64_i32 v[36:37], s[24:25], v34, s31, 0
	v_lshl_add_u64 v[40:41], s[84:85], 0, v[40:41]
	s_waitcnt vmcnt(1)
	v_pk_add_f32 v[32:33], v[32:33], v[44:45]
	v_pk_add_f32 v[30:31], v[30:31], v[42:43]
	s_waitcnt vmcnt(0)
	v_pk_add_f32 v[28:29], v[28:29], v[48:49]
	v_pk_add_f32 v[26:27], v[26:27], v[46:47]
	global_store_dwordx4 v[40:41], v[30:33], off nt
	global_store_dwordx4 v[40:41], v[26:29], off offset:16 nt
	s_cbranch_vccnz .LBB0_843
	v_lshl_add_u64 v[46:47], s[6:7], 0, v[36:37]
	v_lshl_add_u64 v[46:47], v[140:141], 1, v[46:47]
	v_add_co_u32_e32 v46, vcc, 0x2000, v46
	v_cvt_pk_bf16_f32 v42, v30, v31
	v_cvt_pk_bf16_f32 v43, v32, v33
	v_cvt_pk_bf16_f32 v44, v26, v27
	v_cvt_pk_bf16_f32 v45, v28, v29
	v_addc_co_u32_e32 v47, vcc, 0, v47, vcc
	global_store_dwordx4 v[46:47], v[42:45], off offset:2560
.LBB0_843:
	global_load_dwordx4 v[42:45], v[38:39], off offset:512 nt
	s_nop 0
	global_load_dwordx4 v[46:49], v[38:39], off offset:528 nt
	s_and_b64 vcc, exec, s[44:45]
	s_waitcnt vmcnt(1)
	v_pk_add_f32 v[24:25], v[24:25], v[44:45]
	v_pk_add_f32 v[22:23], v[22:23], v[42:43]
	s_waitcnt vmcnt(0)
	v_pk_add_f32 v[20:21], v[20:21], v[48:49]
	v_pk_add_f32 v[18:19], v[18:19], v[46:47]
	global_store_dwordx4 v[40:41], v[22:25], off offset:512 nt
	global_store_dwordx4 v[40:41], v[18:21], off offset:528 nt
	s_cbranch_vccnz .LBB0_845
	v_lshl_add_u64 v[36:37], s[6:7], 0, v[36:37]
	v_lshl_add_u64 v[36:37], v[140:141], 1, v[36:37]
	v_add_co_u32_e32 v36, vcc, 0x2000, v36
	v_cvt_pk_bf16_f32 v38, v22, v23
	v_cvt_pk_bf16_f32 v39, v24, v25
	v_cvt_pk_bf16_f32 v40, v18, v19
	v_cvt_pk_bf16_f32 v41, v20, v21
	v_addc_co_u32_e32 v37, vcc, 0, v37, vcc
	global_store_dwordx4 v[36:37], v[38:41], off offset:2816

; DI unsigned cvtpk(float lo, float hi) { typedef float f2 __attribute__((ext_vector_type(2))); typedef __bf16 b2 __attribute__((ext_vector_type(2))); f2 v = {lo, hi}; b2 b = __builtin_convertvector(v, b2); return __builtin_bit_cast(unsigned, b); }
;     DI void operator()(f32x4 (&acc)[2][2][4][2], const pg8::GUnit& u, int wr, int wc, int fr, int fq) const {
;     ...
; #pragma unroll
;         for (int ai = 0; ai < 2; ++ai)
; #pragma unroll
;             for (int m = 0; m < 4; ++m) {
;                 const int row = row0 + ai * 128 + m * 16;
;                 const size_t off = (size_t)row * DM + col0;
;                 float q = 0.f;
; #pragma unroll
;                 for (int bj = 0; bj < 2; ++bj) {
;                     const f32x4 b0 = *(const f32x4*)(resid + off + bj * 128), b1 = *(const f32x4*)(resid + off + bj * 128 + 4);
;                     const f32x4 v0 = b0 + acc[ai][bj][m][0], v1 = b1 + acc[ai][bj][m][1];
;                     *(f32x4*)(out + off + bj * 128) = v0; *(f32x4*)(out + off + bj * 128 + 4) = v1;
;                     q += (v0[0] * v0[0] + v0[1] * v0[1]) + (v0[2] * v0[2] + v0[3] * v0[3]) + (v1[0] * v1[0] + v1[1] * v1[1]) + (v1[2] * v1[2] + v1[3] * v1[3]);
;                     if (!last) { u32x4 w; w.x = cvtpk(v0[0], v0[1]); w.y = cvtpk(v0[2], v0[3]); w.z = cvtpk(v1[0], v1[1]); w.w = cvtpk(v1[2], v1[3]);
;                         *(u32x4*)(act + (size_t)row * PITCH + XB_COL + col0 + bj * 128) = w; }
;                 }
.LBB0_847:
	s_or_b64 exec, exec, s[24:25]
	v_add_u32_e32 v18, 0xb0, v142
	s_waitcnt lgkmcnt(0)
	v_ashrrev_i32_e32 v19, 31, v18
	v_lshlrev_b64 v[20:21], 10, v[18:19]
	v_lshl_add_u64 v[20:21], v[20:21], 0, v[140:141]
	v_lshlrev_b64 v[24:25], 2, v[20:21]
	v_lshl_add_u64 v[22:23], s[12:13], 0, v[24:25]
	global_load_dwordx4 v[26:29], v[22:23], off nt
	global_load_dwordx4 v[30:33], v[22:23], off offset:16 nt
	s_and_b64 vcc, exec, s[44:45]
	v_mad_i64_i32 v[20:21], s[24:25], v18, s31, 0
	v_lshl_add_u64 v[24:25], s[84:85], 0, v[24:25]
	s_waitcnt vmcnt(1)
	v_pk_add_f32 v[16:17], v[16:17], v[28:29]
	v_pk_add_f32 v[14:15], v[14:15], v[26:27]
	s_waitcnt vmcnt(0)
	v_pk_add_f32 v[12:13], v[12:13], v[32:33]
	v_pk_add_f32 v[10:11], v[10:11], v[30:31]
	global_store_dwordx4 v[24:25], v[14:17], off nt
	global_store_dwordx4 v[24:25], v[10:13], off offset:16 nt
	s_cbranch_vccnz .LBB0_849
	v_lshl_add_u64 v[30:31], s[6:7], 0, v[20:21]
	v_lshl_add_u64 v[30:31], v[140:141], 1, v[30:31]
	v_add_co_u32_e32 v30, vcc, 0x2000, v30
	v_cvt_pk_bf16_f32 v26, v14, v15
	v_cvt_pk_bf16_f32 v27, v16, v17
	v_cvt_pk_bf16_f32 v28, v10, v11
	v_cvt_pk_bf16_f32 v29, v12, v13
	v_addc_co_u32_e32 v31, vcc, 0, v31, vcc
	global_store_dwordx4 v[30:31], v[26:29], off offset:2560
.LBB0_849:
	global_load_dwordx4 v[26:29], v[22:23], off offset:512 nt
	s_nop 0
	global_load_dwordx4 v[30:33], v[22:23], off offset:528 nt
	s_and_b64 vcc, exec, s[44:45]
	s_waitcnt vmcnt(1)
	v_pk_add_f32 v[8:9], v[8:9], v[28:29]
	v_pk_add_f32 v[6:7], v[6:7], v[26:27]
	s_waitcnt vmcnt(0)
	v_pk_add_f32 v[4:5], v[4:5], v[32:33]
	v_pk_add_f32 v[2:3], v[2:3], v[30:31]
	global_store_dwordx4 v[24:25], v[6:9], off offset:512 nt
	global_store_dwordx4 v[24:25], v[2:5], off offset:528 nt
	s_cbranch_vccnz .LBB0_851
	v_lshl_add_u64 v[20:21], s[6:7], 0, v[20:21]
	v_lshl_add_u64 v[20:21], v[140:141], 1, v[20:21]
	v_add_co_u32_e32 v20, vcc, 0x2000, v20
	v_cvt_pk_bf16_f32 v22, v6, v7
	v_cvt_pk_bf16_f32 v23, v8, v9
	v_cvt_pk_bf16_f32 v24, v2, v3
	v_cvt_pk_bf16_f32 v25, v4, v5
	v_addc_co_u32_e32 v21, vcc, 0, v21, vcc
	global_store_dwordx4 v[20:21], v[22:25], off offset:2816

; DI float row_rstd(const float* ssq, int row) {
;     const f32x4* p = (const f32x4*)(ssq + (size_t)row * 16);
;     const f32x4 a = p[0], b = p[1], c = p[2], d = p[3];
;     const float s = ((a.x + a.y) + (a.z + a.w)) + ((b.x + b.y) + (b.z + b.w)) + ((c.x + c.y) + (c.z + c.w)) + ((d.x + d.y) + (d.z + d.w));
;     return 1.0f / sqrtf(s * (1.0f / DM) + RMS_EPS);
; }
; __global__ void __launch_bounds__(512, 2) hybrid_fwd(Params p) {
;     ...
;     for (int row = gw; row < T; row += 2 * NGW) {
;         const int row2 = (row + NGW < T) ? row + NGW : row;
;         f32x4* xr = (f32x4*)(p.out + (size_t)row * DM) + lane; f32x4* xr2 = (f32x4*)(p.out + (size_t)row2 * DM) + lane;
;         const f32x4* wr_ = (const f32x4*)(p.fnw) + lane;
;         f32x4 v[4], v2[4], w[4];
; #pragma unroll
;         for (int j = 0; j < 4; ++j) { v[j] = xr[64 * j]; v2[j] = xr2[64 * j]; w[j] = wr_[64 * j]; }
;         const float rs = row_rstd(ssq, row), rs2 = row_rstd(ssq, row2);
; #pragma unroll
;         for (int j = 0; j < 4; ++j) { xr[64 * j] = v[j] * rs * w[j]; if (row2 != row) xr2[64 * j] = v2[j] * rs2 * w[j]; }
.LBB0_907:
	s_add_i32 s11, s4, s91
	s_cmp_lt_i32 s11, 0x8000
	s_cselect_b32 s6, s11, s4
	s_ashr_i32 s5, s4, 31
	s_ashr_i32 s7, s6, 31
	s_lshl_b64 s[0:1], s[4:5], 12
	s_lshl_b64 s[2:3], s[6:7], 12
	s_lshl_b64 s[12:13], s[4:5], 6
	s_add_u32 s12, s8, s12
	s_addc_u32 s13, s9, s13
	global_load_dwordx4 v[50:53], v41, s[12:13]
	global_load_dwordx4 v[56:59], v41, s[12:13] offset:16
	global_load_dwordx4 v[60:63], v41, s[12:13] offset:32
	global_load_dwordx4 v[64:67], v41, s[12:13] offset:48
	s_lshl_b64 s[12:13], s[6:7], 6
	s_add_u32 s12, s8, s12
	s_addc_u32 s13, s9, s13
	global_load_dwordx4 v[68:71], v41, s[12:13]
	global_load_dwordx4 v[72:75], v41, s[12:13] offset:16
	global_load_dwordx4 v[76:79], v41, s[12:13] offset:32
	global_load_dwordx4 v[80:83], v41, s[12:13] offset:48
	global_load_dwordx4 v[32:35], v[44:45], off
	global_load_dwordx4 v[24:27], v[44:45], off offset:1024
	global_load_dwordx4 v[12:15], v[44:45], off offset:2048
	global_load_dwordx4 v[0:3], v[44:45], off offset:3072
	v_lshl_add_u64 v[46:47], v[42:43], 0, s[0:1]
	v_lshl_add_u64 v[48:49], v[42:43], 0, s[2:3]
	global_load_dwordx4 v[84:87], v[46:47], off nt
	global_load_dwordx4 v[28:31], v[46:47], off offset:1024 nt
	global_load_dwordx4 v[20:23], v[46:47], off offset:2048 nt
	global_load_dwordx4 v[4:7], v[46:47], off offset:3072 nt
	global_load_dwordx4 v[36:39], v[48:49], off nt
	global_load_dwordx4 v[16:19], v[48:49], off offset:2048 nt
	global_load_dwordx4 v[8:11], v[48:49], off offset:3072 nt
	s_cmp_lg_u32 s4, s6
	s_waitcnt vmcnt(18)
	v_mov_b32_e32 v88, v51
	v_mov_b32_e32 v89, v52
	v_mov_b32_e32 v51, v53
	s_waitcnt vmcnt(17)
	v_mov_b32_e32 v52, v57
	v_mov_b32_e32 v53, v58
	v_mov_b32_e32 v57, v59
	v_pk_add_f32 v[50:51], v[88:89], v[50:51]
	v_pk_add_f32 v[52:53], v[52:53], v[56:57]
	s_waitcnt vmcnt(16)
	v_add_f32_e32 v58, v60, v61
	v_add_f32_e32 v60, v62, v63
	s_waitcnt vmcnt(15)
	v_mov_b32_e32 v59, v66
	v_mov_b32_e32 v61, v67
	v_pk_add_f32 v[50:51], v[50:51], v[50:51] op_sel:[0,1] op_sel_hi:[1,0]
	v_pk_add_f32 v[52:53], v[52:53], v[52:53] op_sel:[0,1] op_sel_hi:[1,0]
	v_pk_add_f32 v[56:57], v[58:59], v[60:61]
	s_waitcnt vmcnt(14)
	v_mov_b32_e32 v58, v69
	v_mov_b32_e32 v59, v70
	v_mov_b32_e32 v69, v71
	s_waitcnt vmcnt(13)
	v_mov_b32_e32 v60, v73
	v_mov_b32_e32 v61, v74
	v_mov_b32_e32 v73, v75
	v_mov_b32_e32 v51, v64
	v_mov_b32_e32 v53, v65
	v_pk_add_f32 v[58:59], v[58:59], v[68:69]
	v_pk_add_f32 v[60:61], v[60:61], v[72:73]
	v_pk_add_f32 v[50:51], v[50:51], v[52:53]
	v_pk_add_f32 v[52:53], v[58:59], v[58:59] op_sel:[0,1] op_sel_hi:[1,0]
	v_pk_add_f32 v[58:59], v[60:61], v[60:61] op_sel:[0,1] op_sel_hi:[1,0]
	v_pk_add_f32 v[50:51], v[50:51], v[56:57]
	s_waitcnt vmcnt(12)
	v_add_f32_e32 v62, v76, v77
	v_add_f32_e32 v66, v78, v79
	s_waitcnt vmcnt(11)
	v_mov_b32_e32 v63, v82
	v_mov_b32_e32 v67, v83
	v_mov_b32_e32 v53, v80
	v_mov_b32_e32 v59, v81
	v_add_f32_e32 v55, v50, v51
	v_pk_add_f32 v[62:63], v[62:63], v[66:67]
	v_pk_add_f32 v[50:51], v[52:53], v[58:59]
	v_fmamk_f32 v52, v55, 0x3a800000, v40
	v_pk_add_f32 v[50:51], v[50:51], v[62:63]
	v_mul_f32_e32 v53, 0x4f800000, v52
	v_cmp_gt_f32_e32 vcc, s10, v52
	v_add_f32_e32 v50, v50, v51
	v_fmamk_f32 v50, v50, 0x3a800000, v40
	v_cndmask_b32_e32 v51, v52, v53, vcc
	v_sqrt_f32_e32 v52, v51
	v_mul_f32_e32 v53, 0x4f800000, v50
	v_cmp_gt_f32_e64 s[0:1], s10, v50
	v_add_u32_e32 v55, -1, v52
	s_nop 0
	v_cndmask_b32_e64 v50, v50, v53, s[0:1]
	v_sqrt_f32_e32 v53, v50
	v_add_u32_e32 v56, 1, v52
	v_fma_f32 v57, -v55, v52, v51
	v_fma_f32 v58, -v56, v52, v51
	v_cmp_ge_f32_e64 s[2:3], 0, v57
	v_add_u32_e32 v57, 1, v53
	s_nop 0
	v_cndmask_b32_e64 v52, v52, v55, s[2:3]
	v_add_u32_e32 v55, -1, v53
	v_cmp_lt_f32_e64 s[2:3], 0, v58
	v_fma_f32 v58, -v57, v53, v50
	s_nop 0
	v_cndmask_b32_e64 v52, v52, v56, s[2:3]
	v_fma_f32 v56, -v55, v53, v50
	v_mul_f32_e32 v59, 0x37800000, v52
	v_cmp_ge_f32_e64 s[2:3], 0, v56
	v_cndmask_b32_e32 v52, v52, v59, vcc
	v_cmp_lt_f32_e32 vcc, 0, v58
	v_cndmask_b32_e64 v53, v53, v55, s[2:3]
	s_nop 0
	v_cndmask_b32_e32 v53, v53, v57, vcc
	v_cmp_class_f32_e32 vcc, v51, v54
	s_nop 1
	v_cndmask_b32_e32 v51, v52, v51, vcc
	v_div_scale_f32 v55, s[2:3], v51, v51, 1.0
	v_rcp_f32_e32 v57, v55
	v_mul_f32_e32 v52, 0x37800000, v53
	v_cndmask_b32_e64 v52, v53, v52, s[0:1]
	v_cmp_class_f32_e64 s[0:1], v50, v54
	v_div_scale_f32 v56, vcc, 1.0, v51, 1.0
	s_nop 0
	v_cndmask_b32_e64 v52, v52, v50, s[0:1]
	v_fma_f32 v50, -v55, v57, 1.0
	v_fmac_f32_e32 v57, v50, v57
	v_mul_f32_e32 v50, v56, v57
	v_fma_f32 v53, -v55, v50, v56
	v_fmac_f32_e32 v50, v53, v57
	v_fma_f32 v53, -v55, v50, v56
	v_div_scale_f32 v55, s[0:1], v52, v52, 1.0
	v_rcp_f32_e32 v56, v55
	v_div_fmas_f32 v50, v53, v57, v50
	v_div_fixup_f32 v50, v50, v51, 1.0
	s_cselect_b64 s[0:1], -1, 0
	v_fma_f32 v51, -v55, v56, 1.0
	v_fmac_f32_e32 v56, v51, v56
	v_div_scale_f32 v51, vcc, 1.0, v52, 1.0
	v_mul_f32_e32 v53, v51, v56
	v_fma_f32 v57, -v55, v53, v51
	v_fmac_f32_e32 v53, v57, v56
	v_fma_f32 v51, -v55, v53, v51
	v_div_fmas_f32 v51, v51, v56, v53
	v_div_fixup_f32 v52, v51, v52, 1.0
	v_mov_b32_e32 v51, v50
	s_waitcnt vmcnt(6)
	v_pk_mul_f32 v[56:57], v[50:51], v[84:85] op_sel_hi:[0,1]
	v_pk_mul_f32 v[58:59], v[50:51], v[86:87] op_sel_hi:[0,1]
	s_cmp_eq_u32 s4, s6
	v_mov_b32_e32 v53, v52
	v_pk_mul_f32 v[58:59], v[58:59], v[34:35]
	v_pk_mul_f32 v[56:57], v[56:57], v[32:33]
	s_mov_b64 s[2:3], -1
	s_waitcnt vmcnt(5)
	v_pk_mul_f32 v[28:29], v[50:51], v[28:29]
	global_store_dwordx4 v[46:47], v[56:59], off nt
	s_cbranch_scc1 .LBB0_909
	global_load_dwordx4 v[56:59], v[48:49], off offset:1024 nt
	v_mov_b32_e32 v60, v52
	v_mov_b32_e32 v61, v52
	s_waitcnt vmcnt(4)
	v_pk_mul_f32 v[62:63], v[52:53], v[36:37]
	v_mov_b32_e32 v64, v50
	v_mov_b32_e32 v65, v50
	v_pk_mul_f32 v[38:39], v[60:61], v[38:39]
	v_pk_mul_f32 v[36:37], v[28:29], v[24:25]
	v_pk_mul_f32 v[32:33], v[32:33], v[62:63]
	v_pk_mul_f32 v[62:63], v[64:65], v[30:31]
	v_pk_mul_f32 v[34:35], v[34:35], v[38:39]
	v_pk_mul_f32 v[38:39], v[62:63], v[26:27]
	global_store_dwordx4 v[48:49], v[32:35], off nt
	global_store_dwordx4 v[46:47], v[36:39], off offset:1024 nt
	s_mov_b64 s[2:3], 0
	s_waitcnt vmcnt(2)
	v_pk_mul_f32 v[32:33], v[60:61], v[58:59]
	v_pk_mul_f32 v[36:37], v[52:53], v[56:57]
	v_pk_mul_f32 v[34:35], v[26:27], v[32:33]
	v_pk_mul_f32 v[32:33], v[24:25], v[36:37]
	global_store_dwordx4 v[48:49], v[32:35], off offset:1024 nt
; __global__ void __launch_bounds__(512, 2) hybrid_fwd(Params p) {
;     ...
;     for (int row = gw; row < T; row += 2 * NGW) {
;         const int row2 = (row + NGW < T) ? row + NGW : row;
;         f32x4* xr = (f32x4*)(p.out + (size_t)row * DM) + lane; f32x4* xr2 = (f32x4*)(p.out + (size_t)row2 * DM) + lane;
;         const f32x4* wr_ = (const f32x4*)(p.fnw) + lane;
;         f32x4 v[4], v2[4], w[4];
; #pragma unroll
;         for (int j = 0; j < 4; ++j) { v[j] = xr[64 * j]; v2[j] = xr2[64 * j]; w[j] = wr_[64 * j]; }
;         const float rs = row_rstd(ssq, row), rs2 = row_rstd(ssq, row2);
; #pragma unroll
;         for (int j = 0; j < 4; ++j) { xr[64 * j] = v[j] * rs * w[j]; if (row2 != row) xr2[64 * j] = v2[j] * rs2 * w[j]; }
;     }
.LBB0_909:
	s_andn2_b64 vcc, exec, s[2:3]
	s_cbranch_vccnz .LBB0_911
	v_mov_b32_e32 v32, v50
	v_mov_b32_e32 v33, v50
	v_pk_mul_f32 v[30:31], v[32:33], v[30:31]
	v_pk_mul_f32 v[24:25], v[28:29], v[24:25]
	v_pk_mul_f32 v[26:27], v[30:31], v[26:27]
	global_store_dwordx4 v[46:47], v[24:27], off offset:1024 nt
.LBB0_911:
	s_nop 1
	v_mov_b32_e32 v24, v50
	v_mov_b32_e32 v25, v50
	s_waitcnt vmcnt(5)
	v_pk_mul_f32 v[22:23], v[24:25], v[22:23]
	v_pk_mul_f32 v[20:21], v[50:51], v[20:21]
	v_pk_mul_f32 v[22:23], v[22:23], v[14:15]
	v_pk_mul_f32 v[20:21], v[20:21], v[12:13]
	s_mov_b64 s[2:3], -1
	s_andn2_b64 vcc, exec, s[0:1]
	s_waitcnt vmcnt(4)
	v_pk_mul_f32 v[4:5], v[50:51], v[4:5]
	global_store_dwordx4 v[46:47], v[20:23], off offset:2048 nt
	s_cbranch_vccz .LBB0_913
	s_andn2_b64 vcc, exec, s[2:3]
	s_cbranch_vccnz .LBB0_906
	s_branch .LBB0_914
.LBB0_913:
	s_nop 0
	v_mov_b32_e32 v20, v52
	v_mov_b32_e32 v21, v52
	s_waitcnt vmcnt(3)
	v_pk_mul_f32 v[18:19], v[20:21], v[18:19]
	v_pk_mul_f32 v[16:17], v[52:53], v[16:17]
	v_pk_mul_f32 v[14:15], v[14:15], v[18:19]
	v_pk_mul_f32 v[12:13], v[12:13], v[16:17]
	global_store_dwordx4 v[48:49], v[12:15], off offset:2048 nt
	s_waitcnt vmcnt(3)
	v_pk_mul_f32 v[10:11], v[20:21], v[10:11]
	v_pk_mul_f32 v[8:9], v[52:53], v[8:9]
	v_pk_mul_f32 v[12:13], v[24:25], v[6:7]
	v_pk_mul_f32 v[10:11], v[2:3], v[10:11]
	v_pk_mul_f32 v[14:15], v[12:13], v[2:3]
	v_pk_mul_f32 v[12:13], v[4:5], v[0:1]
	v_pk_mul_f32 v[8:9], v[0:1], v[8:9]
	global_store_dwordx4 v[46:47], v[12:15], off offset:3072 nt
	global_store_dwordx4 v[48:49], v[8:11], off offset:3072 nt
	s_cbranch_execnz .LBB0_906
.LBB0_914:
	v_mov_b32_e32 v51, v50
	v_pk_mul_f32 v[6:7], v[50:51], v[6:7]
	v_pk_mul_f32 v[0:1], v[4:5], v[0:1]
	v_pk_mul_f32 v[2:3], v[6:7], v[2:3]
	global_store_dwordx4 v[46:47], v[0:3], off offset:3072 nt
	s_branch .LBB0_906
